# attention loop counted waits: K staging writes wait vmcnt(5)/vmcnt(4) (only their own loads), V loads waited with vmcnt(0) after the barrier; prologue re-issues the V tile-1 loads so the first iterati
# baseline (speedup 1.0000x reference)
; __device__ __forceinline__ int tidx() { int t = threadIdx.x; asm volatile("" : "+v"(t)); return t; }
; __device__ __forceinline__ void attn_dv256_body(const bf16* __restrict__ Qb, const bf16* __restrict__ Kh, const bf16* __restrict__ Vh,
;                                                 float* __restrict__ Ob, int seq, float kmax, char* lds) {
;   using St = Stage<bf16>;
;   const int tid = tidx(), wid = tid >> 6, lane = tid & 63, r32 = lane & 31, hi = lane >> 5;
;   const int rg = wid & 3, kh = wid >> 2;
;   char* V_lds = lds; char* K_lds = lds + 65536; char* XCH = lds + 98304; float* LI = (float*)(lds + 131072);
;   f32x16 o[4] = {}; bf16x8 qr[8];
;   const bf16* Qw = Qb + (long)(rg * 32 + r32) * LDQ + hi * 8;
; #pragma unroll
;   for (int d0 = 0; d0 < 8; ++d0) qr[d0] = St::ld8(Qw + d0 * 16);
;   float qq = 0.f;
; #pragma unroll
;   for (int d0 = 0; d0 < 8; ++d0)
; #pragma unroll
;     for (int e = 0; e < 8; ++e) { const float v = __uint_as_float(((unsigned)(unsigned short)qr[d0][e]) << 16); qq += v * v; }
;   qq += __shfl_xor(qq, 32);
;   constexpr float C = SCALE * 1.4426950408889634f;
;   const float mC = -sqrtf(qq) * kmax * C * 1.002f;
; __device__ __forceinline__ void attn_item(const u16* P, float* AO, const unsigned* kmaxu, int item, char* lds) {
;     int hm, qrow0, krow0, seq;
;     if (item < 512) { hm = item >> 6; qrow0 = (item & 63) * 128; krow0 = 0; seq = TT; }
;     else { hm = (item - 512) >> 1; qrow0 = TL + ((item - 512) & 1) * 128; krow0 = TL; seq = TC; }
;     const int h = hm >> 1;
;     const att::bf16* Pb = (const att::bf16*)P;
;     const att::bf16* Q = Pb + (size_t)qrow0 * PST + C_CQ + hm * 128;
;     const att::bf16* K = Pb + (size_t)krow0 * PST + C_CK + hm * 128;
;     const att::bf16* V = Pb + (size_t)krow0 * PST + C_CV + h * 256;
;     float* O = AO + (size_t)qrow0 * DM + hm * 256;
;     const float kmax = sqrtf(__uint_as_float(kmaxu[hm]));
;     att::attn_dv256_body(Q, K, V, O, seq, kmax, lds);
.LBB0_909:
	s_mul_i32 s7, s84, 0x4080
	s_mul_hi_u32 s1, s84, 0x4080
	s_add_u32 s7, s78, s7
	s_addc_u32 s1, s79, s1
	s_lshl_b32 s22, s34, 7
	s_ashr_i32 s23, s22, 31
	s_lshl_b64 s[38:39], s[22:23], 1
	s_add_u32 s42, s7, s38
	s_addc_u32 s43, s1, s39
	s_lshl_b32 s0, s0, 1
	s_add_u32 s7, s78, s0
	s_addc_u32 s13, s79, 0
	s_add_u32 s0, s7, s38
	s_addc_u32 s1, s13, s39
	s_add_u32 s38, s0, 0x2800
	s_addc_u32 s39, s1, 0
	s_and_b32 s0, s22, 0xffffff00
	s_ashr_i32 s1, s0, 31
	s_lshl_b64 s[0:1], s[0:1], 1
	s_add_u32 s0, s7, s0
	s_addc_u32 s1, s13, s1
	s_add_u32 s40, s0, 0x3000
	s_addc_u32 s41, s1, 0
	s_ashr_i32 s35, s34, 31
	s_lshl_b64 s[0:1], s[34:35], 2
	s_add_u32 s0, s20, s0
	s_addc_u32 s1, s21, s1
	v_mov_b32_e32 v3, v170
	global_load_dword v6, v165, s[0:1]
	s_mov_b64 s[0:1], 0x2000
	v_ashrrev_i32_e32 v2, 6, v3
	v_lshlrev_b32_e32 v0, 5, v2
	v_and_b32_e32 v186, 31, v3
	v_and_b32_e32 v185, 0x60, v0
	v_or_b32_e32 v0, v185, v186
	v_mul_u32_u24_e32 v0, 0x2040, v0
	v_bfe_u32 v184, v3, 5, 1
	v_lshlrev_b32_e32 v164, 1, v0
	v_lshl_add_u64 v[0:1], s[42:43], 0, v[164:165]
	v_lshlrev_b32_e32 v164, 4, v184
	v_lshl_add_u64 v[0:1], v[0:1], 0, v[164:165]
	v_add_co_u32_e32 v4, vcc, s95, v0
	s_mov_b32 s22, 0xf800000
	s_nop 0
	v_addc_co_u32_e32 v5, vcc, 0, v1, vcc
	global_load_dwordx4 v[80:83], v[4:5], off
	v_lshl_add_u64 v[0:1], v[0:1], 0, s[0:1]
	global_load_dwordx4 v[84:87], v[0:1], off offset:32
	global_load_dwordx4 v[88:91], v[0:1], off offset:64
	global_load_dwordx4 v[92:95], v[0:1], off offset:96
	global_load_dwordx4 v[96:99], v[0:1], off offset:128
	global_load_dwordx4 v[100:103], v[0:1], off offset:160
	global_load_dwordx4 v[104:107], v[0:1], off offset:192
	global_load_dwordx4 v[108:111], v[0:1], off offset:224
	v_ashrrev_i32_e32 v189, 4, v3
	v_add_u32_e32 v190, 32, v189
	s_movk_i32 s13, 0x2040
	s_cmp_lg_u32 0, -1
	v_ashrrev_i32_e32 v187, 8, v3
	v_and_b32_e32 v191, 63, v3
	v_lshlrev_b32_e32 v205, 4, v191
	v_mov_b32_e32 v132, 0
	v_mov_b32_e32 v144, 0
	v_mov_b32_e32 v192, 0
	s_mov_b32 s7, 0
	v_lshlrev_b32_e32 v209, 11, v2
	v_mov_b32_e32 v2, v192
	v_mov_b32_e32 v55, v192
	v_mov_b32_e32 v56, v192
	v_mov_b32_e32 v57, v192
	v_mov_b32_e32 v58, v192
	v_mov_b32_e32 v59, v192
	v_mov_b32_e32 v60, v192
	v_mov_b32_e32 v61, v192
	v_mov_b32_e32 v62, v192
	v_mov_b32_e32 v63, v192
	v_mov_b32_e32 v145, v144
	v_mov_b32_e32 v146, v144
	v_mov_b32_e32 v147, v144
	v_mov_b32_e32 v148, v144
	v_mov_b32_e32 v149, v144
	v_mov_b32_e32 v150, v144
	v_mov_b32_e32 v151, v144
	v_mov_b32_e32 v133, v132
	v_mov_b32_e32 v134, v132
	v_mov_b32_e32 v135, v132
	v_mov_b32_e32 v128, v132
	v_mov_b32_e32 v129, v132
	v_mov_b32_e32 v130, v132
	v_mov_b32_e32 v131, v132
	s_waitcnt vmcnt(8)
	v_mul_f32_e32 v4, 0x4f800000, v6
	v_cmp_gt_f32_e32 vcc, s22, v6
	s_waitcnt vmcnt(6)
	v_lshlrev_b32_e32 v14, 16, v84
	v_cndmask_b32_e32 v4, v6, v4, vcc
	v_sqrt_f32_e32 v7, v4
	v_lshlrev_b32_e32 v8, 16, v81
	v_and_b32_e32 v9, 0xffff0000, v81
	v_lshlrev_b32_e32 v10, 16, v82
	v_add_u32_e32 v0, -1, v7
	v_fma_f32 v1, -v0, v7, v4
	v_add_u32_e32 v5, 1, v7
	v_cmp_ge_f32_e64 s[0:1], 0, v1
	v_and_b32_e32 v1, 0xffff0000, v80
	v_fma_f32 v6, -v5, v7, v4
	v_cndmask_b32_e64 v7, v7, v0, s[0:1]
	v_lshlrev_b32_e32 v0, 16, v80
	v_mul_f32_e32 v54, v1, v1
	v_fmac_f32_e32 v54, v0, v0
	v_fmac_f32_e32 v54, v8, v8
	v_fmac_f32_e32 v54, v9, v9
	v_and_b32_e32 v11, 0xffff0000, v82
	v_fmac_f32_e32 v54, v10, v10
	v_lshlrev_b32_e32 v12, 16, v83
	v_fmac_f32_e32 v54, v11, v11
	v_and_b32_e32 v13, 0xffff0000, v83
	v_fmac_f32_e32 v54, v12, v12
	v_fmac_f32_e32 v54, v13, v13
	v_and_b32_e32 v15, 0xffff0000, v84
	v_fmac_f32_e32 v54, v14, v14
	v_lshlrev_b32_e32 v16, 16, v85
	v_fmac_f32_e32 v54, v15, v15
	v_and_b32_e32 v17, 0xffff0000, v85
	v_fmac_f32_e32 v54, v16, v16
	v_lshlrev_b32_e32 v18, 16, v86
	v_fmac_f32_e32 v54, v17, v17
	v_and_b32_e32 v19, 0xffff0000, v86
	v_fmac_f32_e32 v54, v18, v18
	v_lshlrev_b32_e32 v20, 16, v87
	v_fmac_f32_e32 v54, v19, v19
	v_and_b32_e32 v21, 0xffff0000, v87
	v_fmac_f32_e32 v54, v20, v20
	s_waitcnt vmcnt(5)
	v_lshlrev_b32_e32 v22, 16, v88
	v_fmac_f32_e32 v54, v21, v21
	v_and_b32_e32 v23, 0xffff0000, v88
	v_fmac_f32_e32 v54, v22, v22
	v_lshlrev_b32_e32 v24, 16, v89
	v_fmac_f32_e32 v54, v23, v23
	v_and_b32_e32 v25, 0xffff0000, v89
	v_fmac_f32_e32 v54, v24, v24
	v_lshlrev_b32_e32 v26, 16, v90
	v_fmac_f32_e32 v54, v25, v25
	v_and_b32_e32 v27, 0xffff0000, v90
	v_fmac_f32_e32 v54, v26, v26
	v_lshlrev_b32_e32 v28, 16, v91
	v_fmac_f32_e32 v54, v27, v27
	v_and_b32_e32 v29, 0xffff0000, v91
	v_fmac_f32_e32 v54, v28, v28
	s_waitcnt vmcnt(4)
	v_lshlrev_b32_e32 v30, 16, v92
	v_fmac_f32_e32 v54, v29, v29
	v_and_b32_e32 v31, 0xffff0000, v92
	v_fmac_f32_e32 v54, v30, v30
	v_lshlrev_b32_e32 v32, 16, v93
	v_fmac_f32_e32 v54, v31, v31
	v_and_b32_e32 v33, 0xffff0000, v93
	v_fmac_f32_e32 v54, v32, v32
	v_lshlrev_b32_e32 v34, 16, v94
	v_fmac_f32_e32 v54, v33, v33
	v_and_b32_e32 v35, 0xffff0000, v94
	v_fmac_f32_e32 v54, v34, v34
	v_lshlrev_b32_e32 v36, 16, v95
	v_fmac_f32_e32 v54, v35, v35
	v_and_b32_e32 v37, 0xffff0000, v95
	v_fmac_f32_e32 v54, v36, v36
	s_waitcnt vmcnt(3)
	v_lshlrev_b32_e32 v38, 16, v96
	v_fmac_f32_e32 v54, v37, v37
	v_and_b32_e32 v39, 0xffff0000, v96
	v_fmac_f32_e32 v54, v38, v38
	v_lshlrev_b32_e32 v40, 16, v97
	v_fmac_f32_e32 v54, v39, v39
	v_and_b32_e32 v41, 0xffff0000, v97
	v_fmac_f32_e32 v54, v40, v40
	v_lshlrev_b32_e32 v42, 16, v98
	v_fmac_f32_e32 v54, v41, v41
	v_and_b32_e32 v43, 0xffff0000, v98
	v_fmac_f32_e32 v54, v42, v42
	v_lshlrev_b32_e32 v44, 16, v99
	v_fmac_f32_e32 v54, v43, v43
	v_and_b32_e32 v45, 0xffff0000, v99
	v_fmac_f32_e32 v54, v44, v44
	s_waitcnt vmcnt(2)
; __device__ __forceinline__ int v_st(int k, int c) { const int kk = (k & ~0xC) | ((k & 4) << 1) | ((k & 8) >> 1); return ((kk >> 3) * 4 + (c >> 5)) * 512 + ((kk & 7) * 32 + (c & 31)) * 2; }
; __device__ __forceinline__ int v_rd_base(int lane) { return ((lane & 3) << 3) | (((lane >> 2) & 3) << 6) | (((lane >> 4) & 1) << 5) | (((lane >> 5) & 1) << 8); }
; #define KLOAD(k0) do { kr0 = St::ld8(&Kh[(long)((k0) + sr) * LDK + sc]); kr1 = St::ld8(&Kh[(long)((k0) + 32 + sr) * LDK + sc]); } while (0)
; #define VLOAD(k0) do { vr0 = St::ld8(&Vh[(long)((k0) + sr) * LDK + sc]); vr1 = St::ld8(&Vh[(long)((k0) + 32 + sr) * LDK + sc]); \
;     vr2 = St::ld8(&Vh[(long)((k0) + sr) * LDK + 128 + sc]); vr3 = St::ld8(&Vh[(long)((k0) + 32 + sr) * LDK + 128 + sc]); } while (0)
; #define KWRITE(b) do { *(bf16x8*)(K_lds + (b) * 16384 + KSWZ(sr, sc * 2)) = kr0; *(bf16x8*)(K_lds + (b) * 16384 + KSWZ(32 + sr, sc * 2)) = kr1; } while (0)
; #define VWRITE(b) do { *(bf16x8*)(V_lds + ((b) * 2) * 16384 + vst0) = vr0; *(bf16x8*)(V_lds + ((b) * 2) * 16384 + vst1) = vr1; \
;     *(bf16x8*)(V_lds + ((b) * 2 + 1) * 16384 + vst1) = vr2; *(bf16x8*)(V_lds + ((b) * 2 + 1) * 16384 + vst0) = vr3; } while (0)
; __device__ __forceinline__ void attn_dv256_body(const bf16* __restrict__ Qb, const bf16* __restrict__ Kh, const bf16* __restrict__ Vh,
;                                                 float* __restrict__ Ob, int seq, float kmax, char* lds) {
;     ...
;   float qq = 0.f;
; #pragma unroll
;   for (int d0 = 0; d0 < 8; ++d0)
; #pragma unroll
;     for (int e = 0; e < 8; ++e) { const float v = __uint_as_float(((unsigned)(unsigned short)qr[d0][e]) << 16); qq += v * v; }
;   qq += __shfl_xor(qq, 32);
;   constexpr float C = SCALE * 1.4426950408889634f;
;   const float mC = -sqrtf(qq) * kmax * C * 1.002f;
;   float l_reg = 0.f;
;   const int sr = tid >> 4, sc = (tid & 15) * 8, vst0 = v_st(sr, sc), vst1 = v_st(32 + sr, sc);
;   const int vb0 = (int)(uintptr_t)V_lds + kh * 16384 + v_rd_base(lane);
;   bf16x8 kr0, kr1, vr0, vr1, vr2, vr3;
;     ...
;   const int NT = seq / KVBLK;
;   f32x16 pc, pn; pn = f32x16{};
;   bf16x8 q0 = {}, q1 = {}, q2 = {}, q3 = {};
;   char* XC0 = XCH;
;   KLOAD(0); VLOAD(0); asm volatile("s_waitcnt vmcnt(0)" ::: "memory"); KWRITE(0); VWRITE(0);
;   KLOAD(KVBLK); VLOAD(KVBLK); asm volatile("s_waitcnt vmcnt(0)" ::: "memory"); KWRITE(1); VWRITE(1);
;   __syncthreads();
	v_lshlrev_b32_e32 v46, 16, v100
	v_fmac_f32_e32 v54, v45, v45
	v_and_b32_e32 v47, 0xffff0000, v100
	v_fmac_f32_e32 v54, v46, v46
	v_lshlrev_b32_e32 v48, 16, v101
	v_fmac_f32_e32 v54, v47, v47
	v_and_b32_e32 v49, 0xffff0000, v101
	v_fmac_f32_e32 v54, v48, v48
	v_lshlrev_b32_e32 v50, 16, v102
	v_fmac_f32_e32 v54, v49, v49
	v_lshlrev_b32_e32 v49, 3, v3
	v_and_b32_e32 v51, 0xffff0000, v102
	v_fmac_f32_e32 v54, v50, v50
	v_and_b32_e32 v32, 0x78, v49
	v_mov_b32_e32 v33, v165
	v_lshlrev_b32_e32 v52, 16, v103
	v_fmac_f32_e32 v54, v51, v51
	v_mad_i64_i32 v[8:9], s[0:1], v189, s13, v[32:33]
	v_mad_i64_i32 v[10:11], s[0:1], v190, s13, v[32:33]
	v_and_b32_e32 v53, 0xffff0000, v103
	v_fmac_f32_e32 v54, v52, v52
	v_lshlrev_b64 v[16:17], 1, v[8:9]
	v_lshlrev_b64 v[18:19], 1, v[10:11]
	v_fmac_f32_e32 v54, v53, v53
	s_waitcnt vmcnt(1)
	v_lshlrev_b32_e32 v0, 16, v104
	v_lshl_add_u64 v[8:9], s[38:39], 0, v[16:17]
	v_lshl_add_u64 v[12:13], s[38:39], 0, v[18:19]
	v_fmac_f32_e32 v54, v0, v0
	v_and_b32_e32 v0, 0xffff0000, v104
	v_mad_i64_i32 v[24:25], s[0:1], v189, s13, 0
	v_mad_i64_i32 v[26:27], s[0:1], v190, s13, 0
	global_load_dwordx4 v[8:11], v[8:9], off
	s_nop 0
	global_load_dwordx4 v[12:15], v[12:13], off
	v_add_u32_e32 v34, 64, v189
	v_add_u32_e32 v36, 0x60, v189
	v_fmac_f32_e32 v54, v0, v0
	v_lshlrev_b32_e32 v0, 1, v32
	v_lshl_add_u64 v[24:25], v[24:25], 1, s[40:41]
	v_mov_b32_e32 v1, v165
	v_lshl_add_u64 v[26:27], v[26:27], 1, s[40:41]
	v_mad_i64_i32 v[40:41], s[0:1], v34, s13, 0
	v_mad_i64_i32 v[34:35], s[0:1], v34, s13, v[32:33]
	v_mad_i64_i32 v[32:33], s[0:1], v36, s13, v[32:33]
	v_lshl_add_u64 v[16:17], s[40:41], 0, v[16:17]
	v_lshl_add_u64 v[20:21], s[40:41], 0, v[18:19]
	v_lshl_add_u64 v[24:25], v[24:25], 0, v[0:1]
	v_lshl_add_u64 v[28:29], v[26:27], 0, v[0:1]
	v_lshlrev_b64 v[42:43], 1, v[34:35]
	v_lshlrev_b64 v[46:47], 1, v[32:33]
	global_load_dwordx4 v[16:19], v[16:17], off
	s_nop 0
	global_load_dwordx4 v[20:23], v[20:21], off
	s_nop 0
	global_load_dwordx4 v[24:27], v[24:25], off offset:256
	s_nop 0
	global_load_dwordx4 v[28:31], v[28:29], off offset:256
	s_waitcnt vmcnt(0)
	v_lshl_add_u64 v[34:35], s[38:39], 0, v[42:43]
	v_mad_i64_i32 v[44:45], s[0:1], v36, s13, 0
	v_lshl_add_u64 v[36:37], s[38:39], 0, v[46:47]
	v_lshl_add_u64 v[42:43], s[40:41], 0, v[42:43]
	v_lshl_add_u64 v[40:41], v[40:41], 1, s[40:41]
	global_load_dwordx4 v[32:35], v[34:35], off
	s_nop 0
	global_load_dwordx4 v[36:39], v[36:37], off
	v_lshl_add_u64 v[46:47], s[40:41], 0, v[46:47]
	global_load_dwordx4 v[116:119], v[42:43], off
	global_load_dwordx4 v[112:115], v[46:47], off
	v_lshl_add_u64 v[40:41], v[40:41], 0, v[0:1]
	v_lshl_add_u64 v[42:43], v[44:45], 1, s[40:41]
	v_lshl_add_u64 v[42:43], v[42:43], 0, v[0:1]
	global_load_dwordx4 v[120:123], v[40:41], off offset:256
	global_load_dwordx4 v[124:127], v[42:43], off offset:256
	v_lshlrev_b32_e32 v48, 16, v105
	v_fmac_f32_e32 v54, v48, v48
	v_and_b32_e32 v40, 0xffff0000, v105
	v_fmac_f32_e32 v54, v40, v40
	v_lshlrev_b32_e32 v40, 16, v106
	v_fmac_f32_e32 v54, v40, v40
	v_and_b32_e32 v40, 0xffff0000, v106
	v_fmac_f32_e32 v54, v40, v40
	v_lshlrev_b32_e32 v40, 16, v107
	v_fmac_f32_e32 v54, v40, v40
	v_and_b32_e32 v40, 0xffff0000, v107
	v_and_b32_e32 v41, 0xfffff0, v189
	v_lshlrev_b32_e32 v42, 1, v189
	v_fmac_f32_e32 v54, v40, v40
	s_waitcnt vmcnt(12)
	v_lshlrev_b32_e32 v40, 16, v108
	v_and_or_b32 v41, v42, 8, v41
	v_fmac_f32_e32 v54, v40, v40
	v_and_b32_e32 v40, 0xffff0000, v108
	v_lshrrev_b32_e32 v42, 1, v189
	v_lshrrev_b32_e32 v41, 1, v41
	v_bfe_u32 v43, v49, 5, 2
	v_and_b32_e32 v44, 3, v189
	v_fmac_f32_e32 v54, v40, v40
	v_lshlrev_b32_e32 v40, 16, v109
	v_or_b32_e32 v41, v41, v43
	v_and_or_b32 v42, v42, 4, v44
	v_fmac_f32_e32 v54, v40, v40
	v_and_b32_e32 v40, 0xffff0000, v109
	v_lshlrev_b32_e32 v41, 9, v41
	v_lshlrev_b32_e32 v42, 6, v42
	v_and_b32_e32 v44, 48, v0
	v_fmac_f32_e32 v54, v40, v40
	v_lshlrev_b32_e32 v40, 16, v110
	v_or3_b32 v193, v41, v42, v44
	v_and_b32_e32 v41, 0xfffff0, v190
	v_lshlrev_b32_e32 v45, 1, v190
	v_fmac_f32_e32 v54, v40, v40
	v_and_b32_e32 v40, 0xffff0000, v110
	v_and_or_b32 v41, v45, 8, v41
	v_fmac_f32_e32 v54, v40, v40
	v_lshlrev_b32_e32 v40, 16, v111
	v_lshrrev_b32_e32 v41, 1, v41
	v_fmac_f32_e32 v54, v40, v40
	v_and_b32_e32 v40, 0xffff0000, v111
	v_or_b32_e32 v41, v41, v43
	v_fmac_f32_e32 v54, v40, v40
	v_xor_b32_e32 v40, 32, v171
	v_lshlrev_b32_e32 v41, 9, v41
	v_cmp_lt_i32_e64 s[0:1], v40, v172
	v_or3_b32 v194, v41, v42, v44
	v_lshlrev_b32_e32 v41, 8, v189
	v_and_b32_e32 v42, 0x70, v3
	v_cndmask_b32_e64 v40, v171, v40, s[0:1]
	s_cselect_b32 s13, 0, 0
	v_bfe_u32 v249, v170, 8, 1
	v_lshlrev_b32_e32 v249, 7, v249
	v_bfe_u32 v250, v170, 4, 1
	v_lshlrev_b32_e32 v250, 7, v250
	v_bitop3_b32 v195, v0, v41, v42 bitop3:0xde
	v_xor_b32_e32 v195, v195, v249
	s_add_i32 s0, 0, 0x10000
	v_add_u32_e32 v41, s0, v195
	s_waitcnt vmcnt(11)
	ds_write_b128 v41, v[8:11]
	v_lshlrev_b32_e32 v8, 8, v190
	v_bitop3_b32 v196, v0, v8, v42 bitop3:0xde
	v_xor_b32_e32 v196, v196, v249
	v_add_u32_e32 v8, s0, v196
	s_waitcnt vmcnt(10)
	ds_write_b128 v8, v[12:15]
	v_add_u32_e32 v8, 0, v193
	v_add_u32_e32 v9, 0, v194
	s_add_i32 s1, 0, 0x14000
	s_waitcnt vmcnt(9)
	ds_write_b128 v8, v[16:19]
	s_waitcnt vmcnt(8)
	ds_write_b128 v9, v[20:23]
	s_waitcnt vmcnt(7)
	ds_write_b128 v9, v[24:27] offset:16384
	s_waitcnt vmcnt(6)
	ds_write_b128 v8, v[28:31] offset:16384
	v_add_u32_e32 v10, s1, v195
	s_waitcnt vmcnt(0)
	v_lshlrev_b32_e32 v12, 4, v3
	v_and_b32_e32 v16, 0x70, v12
	v_bitop3_b32 v199, v164, v16, 32 bitop3:0x36
	v_xor_b32_e32 v199, v199, v250
	s_waitcnt vmcnt(5)
	ds_write_b128 v10, v[32:35]
	v_add_u32_e32 v10, s1, v196
	s_waitcnt vmcnt(4)
	ds_write_b128 v10, v[36:39]
	s_waitcnt vmcnt(3)
	ds_write_b128 v8, v[116:119] offset:32768
	s_waitcnt vmcnt(2)
	ds_write_b128 v9, v[112:115] offset:32768
	s_waitcnt vmcnt(1)
	ds_write_b128 v9, v[120:123] offset:49152
	s_waitcnt vmcnt(0)
	ds_write_b128 v8, v[124:127] offset:49152
	v_lshlrev_b32_e32 v8, 13, v187
	v_lshlrev_b32_e32 v9, 8, v186
	v_add3_u32 v197, s0, v8, v9
	s_movk_i32 s0, 0x70
	v_bitop3_b32 v198, v164, v12, s0 bitop3:0x78
	v_xor_b32_e32 v198, v198, v250
	v_add_u32_e32 v8, v197, v198
	s_waitcnt lgkmcnt(0)
	s_barrier
; __device__ __forceinline__ int v_st(int k, int c) { const int kk = (k & ~0xC) | ((k & 4) << 1) | ((k & 8) >> 1); return ((kk >> 3) * 4 + (c >> 5)) * 512 + ((kk & 7) * 32 + (c & 31)) * 2; }
; __device__ __forceinline__ int v_rd_base(int lane) { return ((lane & 3) << 3) | (((lane >> 2) & 3) << 6) | (((lane >> 4) & 1) << 5) | (((lane >> 5) & 1) << 8); }
; #define KLOAD(k0) do { kr0 = St::ld8(&Kh[(long)((k0) + sr) * LDK + sc]); kr1 = St::ld8(&Kh[(long)((k0) + 32 + sr) * LDK + sc]); } while (0)
; #define VLOAD(k0) do { vr0 = St::ld8(&Vh[(long)((k0) + sr) * LDK + sc]); vr1 = St::ld8(&Vh[(long)((k0) + 32 + sr) * LDK + sc]); \
;     vr2 = St::ld8(&Vh[(long)((k0) + sr) * LDK + 128 + sc]); vr3 = St::ld8(&Vh[(long)((k0) + 32 + sr) * LDK + 128 + sc]); } while (0)
; #define KWRITE(b) do { *(bf16x8*)(K_lds + (b) * 16384 + KSWZ(sr, sc * 2)) = kr0; *(bf16x8*)(K_lds + (b) * 16384 + KSWZ(32 + sr, sc * 2)) = kr1; } while (0)
; #define VWRITE(b) do { *(bf16x8*)(V_lds + ((b) * 2) * 16384 + vst0) = vr0; *(bf16x8*)(V_lds + ((b) * 2) * 16384 + vst1) = vr1; \
;     *(bf16x8*)(V_lds + ((b) * 2 + 1) * 16384 + vst1) = vr2; *(bf16x8*)(V_lds + ((b) * 2 + 1) * 16384 + vst0) = vr3; } while (0)
; __device__ __forceinline__ void attn_dv256_body(const bf16* __restrict__ Qb, const bf16* __restrict__ Kh, const bf16* __restrict__ Vh,
;                                                 float* __restrict__ Ob, int seq, float kmax, char* lds) {
;     ...
;   qq += __shfl_xor(qq, 32);
;   constexpr float C = SCALE * 1.4426950408889634f;
;   const float mC = -sqrtf(qq) * kmax * C * 1.002f;
;   float l_reg = 0.f;
;   const int sr = tid >> 4, sc = (tid & 15) * 8, vst0 = v_st(sr, sc), vst1 = v_st(32 + sr, sc);
;   const int vb0 = (int)(uintptr_t)V_lds + kh * 16384 + v_rd_base(lane);
;   bf16x8 kr0, kr1, vr0, vr1, vr2, vr3;
;     ...
;   const int NT = seq / KVBLK;
;   f32x16 pc, pn; pn = f32x16{};
;   bf16x8 q0 = {}, q1 = {}, q2 = {}, q3 = {};
;   char* XC0 = XCH;
;   KLOAD(0); VLOAD(0); asm volatile("s_waitcnt vmcnt(0)" ::: "memory"); KWRITE(0); VWRITE(0);
;   KLOAD(KVBLK); VLOAD(KVBLK); asm volatile("s_waitcnt vmcnt(0)" ::: "memory"); KWRITE(1); VWRITE(1);
;   __syncthreads();
;   QKH(pc, 0);
;   KLOAD((2 < NT ? 2 : NT - 1) * KVBLK);
;   __syncthreads();
	ds_read_b128 v[8:11], v8
	v_cmp_lt_f32_e64 s[0:1], 0, v6
	v_lshlrev_b32_e32 v188, 2, v40
	ds_bpermute_b32 v40, v188, v54
	v_cndmask_b32_e64 v5, v7, v5, s[0:1]
	v_add_u32_e32 v7, v197, v199
	ds_read_b128 v[12:15], v7
	s_waitcnt lgkmcnt(2)
	v_mfma_f32_32x32x16_bf16 v[64:79], v[8:11], v[80:83], 0
	v_mul_f32_e32 v6, 0x37800000, v5
	v_cndmask_b32_e32 v5, v5, v6, vcc
	s_waitcnt lgkmcnt(1)
	v_add_f32_e32 v6, v54, v40
	v_mul_f32_e32 v7, 0x4f800000, v6
	v_cmp_gt_f32_e32 vcc, s22, v6
	v_bitop3_b32 v200, v164, v16, 64 bitop3:0x36
	v_xor_b32_e32 v200, v200, v250
	v_lshlrev_b32_e32 v3, 1, v3
	v_cndmask_b32_e32 v17, v6, v7, vcc
	v_add_u32_e32 v6, v197, v200
	ds_read_b128 v[6:9], v6
	s_waitcnt lgkmcnt(1)
	v_mfma_f32_32x32x16_bf16 v[64:79], v[12:15], v[84:87], v[64:79]
	v_mov_b32_e32 v15, 0x260
	v_cmp_class_f32_e64 s[0:1], v4, v15
	v_sqrt_f32_e32 v18, v17
	v_and_b32_e32 v3, 32, v3
	v_cndmask_b32_e64 v14, v5, v4, s[0:1]
	s_movk_i32 s0, 0x60
	v_bitop3_b32 v201, v164, v16, s0 bitop3:0x36
	v_xor_b32_e32 v201, v201, v250
	v_add_u32_e32 v5, v197, v201
	ds_read_b128 v[10:13], v5
	s_waitcnt lgkmcnt(1)
	v_mfma_f32_32x32x16_bf16 v[64:79], v[6:9], v[88:91], v[64:79]
	v_add_u32_e32 v4, -1, v18
	v_fma_f32 v5, -v4, v18, v17
	v_cmp_ge_f32_e64 s[0:1], 0, v5
	v_add_u32_e32 v9, 1, v18
	v_lshl_add_u64 v[166:167], s[38:39], 0, v[0:1]
	v_cndmask_b32_e64 v8, v18, v4, s[0:1]
	s_movk_i32 s0, 0x80
	v_bitop3_b32 v202, v164, v16, s0 bitop3:0x36
	v_xor_b32_e32 v202, v202, v250
	v_add_u32_e32 v4, v197, v202
	ds_read_b128 v[4:7], v4
	s_waitcnt lgkmcnt(1)
	v_mfma_f32_32x32x16_bf16 v[64:79], v[10:13], v[92:95], v[64:79]
	v_fma_f32 v10, -v9, v18, v17
	v_cmp_lt_f32_e64 s[0:1], 0, v10
	v_lshl_add_u64 v[168:169], s[40:41], 0, v[0:1]
	v_mov_b32_e32 v18, v192
	v_cndmask_b32_e64 v12, v8, v9, s[0:1]
	s_movk_i32 s0, 0xa0
	v_bitop3_b32 v203, v164, v16, s0 bitop3:0x36
	v_xor_b32_e32 v203, v203, v250
	v_add_u32_e32 v8, v197, v203
	ds_read_b128 v[8:11], v8
	s_waitcnt lgkmcnt(1)
	v_mfma_f32_32x32x16_bf16 v[64:79], v[4:7], v[96:99], v[64:79]
	v_mul_f32_e32 v13, 0x37800000, v12
	v_cndmask_b32_e32 v4, v12, v13, vcc
	v_cmp_class_f32_e32 vcc, v17, v15
	s_movk_i32 s0, 0xc0
	v_bitop3_b32 v204, v164, v16, s0 bitop3:0x36
	v_xor_b32_e32 v204, v204, v250
	v_cndmask_b32_e32 v4, v4, v17, vcc
	v_mul_f32_e32 v12, v14, v4
	v_add_u32_e32 v4, v197, v204
	ds_read_b128 v[4:7], v4
	s_waitcnt lgkmcnt(1)
	v_mfma_f32_32x32x16_bf16 v[64:79], v[8:11], v[100:103], v[64:79]
	s_movk_i32 s0, 0xe0
	v_bitop3_b32 v206, v164, v16, s0 bitop3:0x36
	v_xor_b32_e32 v206, v206, v250
	v_add_u32_e32 v8, v197, v206
	v_lshlrev_b32_e32 v14, 3, v191
	ds_read_b128 v[8:11], v8
	v_lshlrev_b32_e32 v13, 14, v187
	v_mul_f32_e32 v12, 0x3e0293ee, v12
	s_waitcnt lgkmcnt(1)
	v_mfma_f32_32x32x16_bf16 v[64:79], v[4:7], v[104:107], v[64:79]
	v_and_b32_e32 v4, 0xc0, v205
	v_and_or_b32 v4, v14, 24, v4
	v_and_b32_e32 v5, 0x100, v14
	v_or3_b32 v3, v4, v3, v5
	v_add3_u32 v207, v13, s13, v3
	v_add_u32_e32 v3, 0x80, v189
	v_mov_b64_e32 v[4:5], s[38:39]
	v_mad_i64_i32 v[6:7], s[22:23], v3, s93, v[4:5]
	v_add_u32_e32 v3, 0xa0, v189
	v_lshl_add_u64 v[6:7], v[6:7], 0, v[0:1]
	v_mad_i64_i32 v[4:5], s[22:23], v3, s93, v[4:5]
	v_lshl_add_u64 v[4:5], v[4:5], 0, v[0:1]
	global_load_dwordx4 v[136:139], v[6:7], off
	global_load_dwordx4 v[140:143], v[4:5], off
	s_waitcnt lgkmcnt(0)
	v_mfma_f32_32x32x16_bf16 v[64:79], v[8:11], v[108:111], v[64:79]
	v_mul_f32_e32 v208, 0xbf804189, v12
	s_add_i32 s0, s6, -1
	v_mov_b32_e32 v0, 0
	v_mov_b32_e32 v1, v192
	v_mov_b32_e32 v3, v192
	v_mov_b32_e32 v4, v192
	v_mov_b32_e32 v5, v192
	v_mov_b32_e32 v6, v192
	v_mov_b32_e32 v7, v192
	v_mov_b32_e32 v8, v192
	v_mov_b32_e32 v9, v192
	v_mov_b32_e32 v10, v192
	v_mov_b32_e32 v11, v192
	v_mov_b32_e32 v12, v192
	v_mov_b32_e32 v13, v192
	v_mov_b32_e32 v14, v192
	v_mov_b32_e32 v15, v192
	v_mov_b32_e32 v16, 0
	v_mov_b32_e32 v17, v192
	v_mov_b32_e32 v19, v192
	v_mov_b32_e32 v20, v192
	v_mov_b32_e32 v21, v192
	v_mov_b32_e32 v22, v192
	v_mov_b32_e32 v23, v192
	v_mov_b32_e32 v24, v192
	v_mov_b32_e32 v25, v192
	v_mov_b32_e32 v26, v192
	v_mov_b32_e32 v27, v192
	v_mov_b32_e32 v28, v192
	v_mov_b32_e32 v29, v192
	v_mov_b32_e32 v30, v192
	v_mov_b32_e32 v31, v192
	v_mov_b32_e32 v32, 0
	v_mov_b32_e32 v33, v192
	v_mov_b32_e32 v34, v192
	v_mov_b32_e32 v35, v192
	v_mov_b32_e32 v36, v192
	v_mov_b32_e32 v37, v192
	v_mov_b32_e32 v38, v192
	v_mov_b32_e32 v39, v192
	v_mov_b32_e32 v40, v192
	v_mov_b32_e32 v41, v192
	v_mov_b32_e32 v42, v192
	v_mov_b32_e32 v43, v192
	v_mov_b32_e32 v44, v192
	v_mov_b32_e32 v45, v192
	v_mov_b32_e32 v46, v192
	v_mov_b32_e32 v47, v192
	v_mov_b32_e32 v48, 0
	v_mov_b32_e32 v49, v192
	v_mov_b32_e32 v50, v192
	v_mov_b32_e32 v51, v192
	v_mov_b32_e32 v52, v192
	v_mov_b32_e32 v53, v192
	v_mov_b32_e32 v54, v192
	s_barrier
	s_min_u32 s100, s0, 1
	s_lshl_b32 s100, s100, 6
	v_add_u32_e32 v116, s100, v189
	v_add_u32_e32 v117, s100, v190
	v_mad_i64_i32 v[120:121], s[22:23], v116, s93, v[168:169]
	v_mad_i64_i32 v[124:125], s[22:23], v117, s93, v[168:169]
	s_nop 0
	global_load_dwordx4 v[112:115], v[124:125], off
	global_load_dwordx4 v[116:119], v[120:121], off
	s_nop 0
	global_load_dwordx4 v[120:123], v[120:121], off offset:256
	global_load_dwordx4 v[124:127], v[124:125], off offset:256
; #define SBAR() __builtin_amdgcn_sched_barrier(0)
; template <int DA, int DB> __device__ __forceinline__ void pv2_issue(PvT& T, int vb) {
;   T.t[0] = tr_read<v_rd_off(DA, 0, 0)>(vb); T.t[1] = tr_read<v_rd_off(DA, 0, 1)>(vb); T.t[2] = tr_read<v_rd_off(DA, 1, 0)>(vb); T.t[3] = tr_read<v_rd_off(DA, 1, 1)>(vb);
;   T.t[4] = tr_read<v_rd_off(DA, 2, 0)>(vb); T.t[5] = tr_read<v_rd_off(DA, 2, 1)>(vb); T.t[6] = tr_read<v_rd_off(DA, 3, 0)>(vb); T.t[7] = tr_read<v_rd_off(DA, 3, 1)>(vb);
;   T.t[8] = tr_read<v_rd_off(DB, 0, 0)>(vb); T.t[9] = tr_read<v_rd_off(DB, 0, 1)>(vb); T.t[10] = tr_read<v_rd_off(DB, 1, 0)>(vb); T.t[11] = tr_read<v_rd_off(DB, 1, 1)>(vb);
;   T.t[12] = tr_read<v_rd_off(DB, 2, 0)>(vb); T.t[13] = tr_read<v_rd_off(DB, 2, 1)>(vb); T.t[14] = tr_read<v_rd_off(DB, 3, 0)>(vb); T.t[15] = tr_read<v_rd_off(DB, 3, 1)>(vb);
; }
; __device__ __forceinline__ void pv2_mma(f32x16& oa, f32x16& ob, const PvT& T, bf16x8 pa0, bf16x8 pa1, bf16x8 pa2, bf16x8 pa3) {
;   asm volatile("s_waitcnt lgkmcnt(0)" ::: "memory"); SBAR();
;     ...
;   oa = __builtin_amdgcn_mfma_f32_32x32x16_bf16(pa0, PK(T.t[0], T.t[1]), oa, 0, 0, 0);
;   ob = __builtin_amdgcn_mfma_f32_32x32x16_bf16(pa0, PK(T.t[8], T.t[9]), ob, 0, 0, 0);
;   oa = __builtin_amdgcn_mfma_f32_32x32x16_bf16(pa1, PK(T.t[2], T.t[3]), oa, 0, 0, 0);
; __device__ __forceinline__ void attn_dv256_body(const bf16* __restrict__ Qb, const bf16* __restrict__ Kh, const bf16* __restrict__ Vh,
;                                                 float* __restrict__ Ob, int seq, float kmax, char* lds) {
;     ...
;   for (int j = 0; j < NT; ++j) {
;     const int b = j & 1;
;     PvT T;
;     pv2_issue<2, 3>(T, vb0 + (b ^ 1) * 32768);
;     QKH(pn, b ^ 1);
;     float ps = 0.f;
; #pragma unroll
;     for (int r = 0; r < 16; ++r) { pc[r] = __builtin_amdgcn_exp2f(fmaf(pc[r], C, mC)); ps += pc[r]; }
;     l_reg += ps;
;     pv2_mma(o[2], o[3], T, q0, q1, q2, q3);
;     pv2_issue<0, 1>(T, vb0 + (b ^ 1) * 32768);
;     bf16x8 own0, own1; PK4(pc, 0, own0); PK4(pc, 8, own1);
;     *(bf16x8*)(XC0 + b * 16384 + ((wid * 2 + 0) * 64 + lane) * 16) = own0; *(bf16x8*)(XC0 + b * 16384 + ((wid * 2 + 1) * 64 + lane) * 16) = own1;
;     KWRITE(b);
;     pv2_mma(o[0], o[1], T, q0, q1, q2, q3);
;     __syncthreads();
;     VWRITE(b ^ 1);
;     { const int kt = (j + 3 < NT) ? j + 3 : NT - 1, vt = (j + 2 < NT) ? j + 2 : NT - 1; KLOAD(kt * KVBLK); VLOAD(vt * KVBLK); }
.LBB0_910:
	s_and_b32 s1, s7, 1
	s_xor_b32 s22, s1, 1
	s_lshl_b32 s13, s22, 15
	v_add_u32_e32 v247, s13, v207
	ds_read_b64_tr_b16 v[152:153], v247 offset:0x400
	ds_read_b64_tr_b16 v[154:155], v247 offset:0xc00
	ds_read_b64_tr_b16 v[156:157], v247 offset:0x1400
	ds_read_b64_tr_b16 v[158:159], v247 offset:0x1c00
	ds_read_b64_tr_b16 v[160:161], v247 offset:0x2400
	ds_read_b64_tr_b16 v[162:163], v247 offset:0x2c00
	ds_read_b64_tr_b16 v[210:211], v247 offset:0x3400
	ds_read_b64_tr_b16 v[212:213], v247 offset:0x3c00
	ds_read_b64_tr_b16 v[214:215], v247 offset:0x600
	ds_read_b64_tr_b16 v[216:217], v247 offset:0xe00
	ds_read_b64_tr_b16 v[218:219], v247 offset:0x1600
	ds_read_b64_tr_b16 v[220:221], v247 offset:0x1e00
	ds_read_b64_tr_b16 v[222:223], v247 offset:0x2600
	ds_read_b64_tr_b16 v[224:225], v247 offset:0x2e00
	v_lshl_add_u32 v246, s22, 14, v197
	ds_read_b64_tr_b16 v[226:227], v247 offset:0x3600
	v_fmamk_f32 v174, v64, 0x3e0293ee, v208
	v_add_u32_e32 v64, v246, v198
	ds_read_b64_tr_b16 v[228:229], v247 offset:0x3e00
	v_fmamk_f32 v175, v65, 0x3e0293ee, v208
	v_fmamk_f32 v181, v66, 0x3e0293ee, v208
	v_fmamk_f32 v182, v67, 0x3e0293ee, v208
	ds_read_b128 v[64:67], v64
	v_fmamk_f32 v238, v68, 0x3e0293ee, v208
	v_add_u32_e32 v68, v246, v199
	ds_read_b128 v[230:233], v68
	v_fmamk_f32 v239, v69, 0x3e0293ee, v208
	v_fmamk_f32 v240, v70, 0x3e0293ee, v208
	v_fmamk_f32 v241, v71, 0x3e0293ee, v208
	v_fmamk_f32 v242, v72, 0x3e0293ee, v208
	v_fmamk_f32 v243, v73, 0x3e0293ee, v208
	v_fmamk_f32 v244, v74, 0x3e0293ee, v208
	v_fmamk_f32 v245, v75, 0x3e0293ee, v208
	v_fmamk_f32 v248, v76, 0x3e0293ee, v208
	v_fmamk_f32 v249, v77, 0x3e0293ee, v208
	v_fmamk_f32 v250, v78, 0x3e0293ee, v208
	v_fmamk_f32 v173, v79, 0x3e0293ee, v208
	s_waitcnt lgkmcnt(1)
	v_mfma_f32_32x32x16_bf16 v[64:79], v[64:67], v[80:83], 0
	v_add_u32_e32 v234, v246, v200
	v_exp_f32_e32 v174, v174
	v_exp_f32_e32 v175, v175
	v_exp_f32_e32 v181, v181
	v_exp_f32_e32 v182, v182
	v_exp_f32_e32 v238, v238
	v_exp_f32_e32 v239, v239
	s_waitcnt lgkmcnt(0)
	v_mfma_f32_32x32x16_bf16 v[64:79], v[230:233], v[84:87], v[64:79]
	ds_read_b128 v[230:233], v234
	v_add_u32_e32 v234, v246, v201
	ds_read_b128 v[234:237], v234
	v_exp_f32_e32 v240, v240
	v_exp_f32_e32 v241, v241
	v_exp_f32_e32 v242, v242
	v_exp_f32_e32 v243, v243
	s_waitcnt lgkmcnt(1)
	v_mfma_f32_32x32x16_bf16 v[64:79], v[230:233], v[88:91], v[64:79]
	v_add_u32_e32 v230, v246, v202
	ds_read_b128 v[230:233], v230
	v_exp_f32_e32 v244, v244
	v_exp_f32_e32 v245, v245
	v_exp_f32_e32 v248, v248
	v_exp_f32_e32 v249, v249
	v_exp_f32_e32 v250, v250
	s_waitcnt lgkmcnt(1)
	v_mfma_f32_32x32x16_bf16 v[64:79], v[234:237], v[92:95], v[64:79]
	v_add_u32_e32 v234, v246, v203
	ds_read_b128 v[234:237], v234
	v_exp_f32_e32 v173, v173
	s_waitcnt lgkmcnt(1)
	v_mfma_f32_32x32x16_bf16 v[64:79], v[230:233], v[96:99], v[64:79]
	v_add_u32_e32 v230, v246, v204
	ds_read_b128 v[230:233], v230
	s_waitcnt lgkmcnt(1)
	v_mfma_f32_32x32x16_bf16 v[64:79], v[234:237], v[100:103], v[64:79]
	v_add_f32_e32 v235, 0, v174
	v_add_f32_e32 v235, v175, v235
	v_add_u32_e32 v234, v246, v206
	v_add_f32_e32 v235, v181, v235
	v_add_f32_e32 v246, v182, v235
	ds_read_b128 v[234:237], v234
	s_waitcnt lgkmcnt(0)
	s_waitcnt lgkmcnt(1)
	v_mfma_f32_32x32x16_bf16 v[64:79], v[230:233], v[104:107], v[64:79]
	v_add_f32_e32 v230, v238, v246
	v_add_f32_e32 v230, v239, v230
	v_add_f32_e32 v230, v240, v230
	v_add_f32_e32 v230, v241, v230
	v_add_f32_e32 v230, v242, v230
	v_add_f32_e32 v230, v243, v230
	v_add_f32_e32 v230, v244, v230
	s_waitcnt lgkmcnt(0)
	v_mfma_f32_32x32x16_bf16 v[64:79], v[234:237], v[108:111], v[64:79]
	v_add_f32_e32 v230, v245, v230
	v_add_f32_e32 v230, v248, v230
	v_add_f32_e32 v230, v249, v230
	v_add_f32_e32 v230, v250, v230
	v_add_f32_e32 v230, v173, v230
	v_add_f32_e32 v192, v192, v230
	v_cvt_pk_bf16_f32 v241, v240, v241
	v_cvt_pk_bf16_f32 v240, v238, v239
	v_cvt_pk_bf16_f32 v239, v181, v182
	v_cvt_pk_bf16_f32 v238, v174, v175
	v_cvt_pk_bf16_f32 v242, v242, v243
	v_cvt_pk_bf16_f32 v243, v244, v245
	v_cvt_pk_bf16_f32 v244, v248, v249
	v_cvt_pk_bf16_f32 v245, v250, v173
	s_lshl_b32 s1, s1, 14
	s_add_i32 s1, s1, 0
	s_add_i32 s35, s1, 0x18000
	s_add_i32 s1, s1, 0x10000
	v_permlane32_swap_b32_e32 v238, v240
	v_permlane32_swap_b32_e32 v239, v241
	v_add3_u32 v173, s35, v209, v205
	v_permlane32_swap_b32_e32 v242, v244
	v_permlane32_swap_b32_e32 v243, v245
	ds_write_b128 v173, v[238:241]
	ds_write_b128 v173, v[242:245] offset:1024
	v_mfma_f32_32x32x16_bf16 v[32:47], v[144:147], v[152:155], v[32:47]
	v_mfma_f32_32x32x16_bf16 v[48:63], v[144:147], v[214:217], v[48:63]
	v_mfma_f32_32x32x16_bf16 v[32:47], v[148:151], v[156:159], v[32:47]
	v_mfma_f32_32x32x16_bf16 v[48:63], v[148:151], v[218:221], v[48:63]
	v_add_u32_e32 v173, s1, v195
	s_waitcnt vmcnt(5)
	ds_write_b128 v173, v[136:139]
	v_add_u32_e32 v136, s1, v196
	s_waitcnt vmcnt(4)
	ds_write_b128 v136, v[140:143]
	v_mfma_f32_32x32x16_bf16 v[32:47], v[132:135], v[160:163], v[32:47]
	v_mfma_f32_32x32x16_bf16 v[48:63], v[132:135], v[222:225], v[48:63]
	v_mfma_f32_32x32x16_bf16 v[32:47], v[128:131], v[210:213], v[32:47]
	ds_read_b64_tr_b16 v[210:211], v247 offset:0
	ds_read_b64_tr_b16 v[212:213], v247 offset:0x800
	ds_read_b64_tr_b16 v[214:215], v247 offset:0x1000
	ds_read_b64_tr_b16 v[216:217], v247 offset:0x1800
	ds_read_b64_tr_b16 v[218:219], v247 offset:0x2000
	ds_read_b64_tr_b16 v[220:221], v247 offset:0x2800
	ds_read_b64_tr_b16 v[222:223], v247 offset:0x3000
	ds_read_b64_tr_b16 v[224:225], v247 offset:0x3800
	v_mfma_f32_32x32x16_bf16 v[48:63], v[128:131], v[226:229], v[48:63]
	ds_read_b64_tr_b16 v[226:227], v247 offset:0x200
	ds_read_b64_tr_b16 v[228:229], v247 offset:0xa00
	ds_read_b64_tr_b16 v[230:231], v247 offset:0x1200
	ds_read_b64_tr_b16 v[232:233], v247 offset:0x1a00
	ds_read_b64_tr_b16 v[234:235], v247 offset:0x2200
	ds_read_b64_tr_b16 v[236:237], v247 offset:0x2a00
	ds_read_b64_tr_b16 v[160:161], v247 offset:0x3200
	ds_read_b64_tr_b16 v[162:163], v247 offset:0x3a00
	s_waitcnt lgkmcnt(0)
	s_add_i32 s1, s13, 0
	s_add_i32 s13, s7, 3
	s_add_i32 s22, s7, 2
	v_add_u32_e32 v136, s1, v193
	v_add_u32_e32 v137, s1, v194
	s_min_u32 s1, s13, s0
	s_min_u32 s13, s22, s0
	s_lshl_b32 s1, s1, 6
	s_lshl_b32 s13, s13, 6
	s_waitcnt lgkmcnt(0)
	s_barrier
; #define SBAR() __builtin_amdgcn_sched_barrier(0)
; #define KLOAD(k0) do { kr0 = St::ld8(&Kh[(long)((k0) + sr) * LDK + sc]); kr1 = St::ld8(&Kh[(long)((k0) + 32 + sr) * LDK + sc]); } while (0)
; #define VLOAD(k0) do { vr0 = St::ld8(&Vh[(long)((k0) + sr) * LDK + sc]); vr1 = St::ld8(&Vh[(long)((k0) + 32 + sr) * LDK + sc]); \
;     vr2 = St::ld8(&Vh[(long)((k0) + sr) * LDK + 128 + sc]); vr3 = St::ld8(&Vh[(long)((k0) + 32 + sr) * LDK + 128 + sc]); } while (0)
; __device__ __forceinline__ void pv2_mma(f32x16& oa, f32x16& ob, const PvT& T, bf16x8 pa0, bf16x8 pa1, bf16x8 pa2, bf16x8 pa3) {
;   asm volatile("s_waitcnt lgkmcnt(0)" ::: "memory"); SBAR();
;     ...
;   oa = __builtin_amdgcn_mfma_f32_32x32x16_bf16(pa0, PK(T.t[0], T.t[1]), oa, 0, 0, 0);
;   ob = __builtin_amdgcn_mfma_f32_32x32x16_bf16(pa0, PK(T.t[8], T.t[9]), ob, 0, 0, 0);
;   oa = __builtin_amdgcn_mfma_f32_32x32x16_bf16(pa1, PK(T.t[2], T.t[3]), oa, 0, 0, 0);
;   ob = __builtin_amdgcn_mfma_f32_32x32x16_bf16(pa1, PK(T.t[10], T.t[11]), ob, 0, 0, 0);
;   oa = __builtin_amdgcn_mfma_f32_32x32x16_bf16(pa2, PK(T.t[4], T.t[5]), oa, 0, 0, 0);
;   ob = __builtin_amdgcn_mfma_f32_32x32x16_bf16(pa2, PK(T.t[12], T.t[13]), ob, 0, 0, 0);
;   oa = __builtin_amdgcn_mfma_f32_32x32x16_bf16(pa3, PK(T.t[6], T.t[7]), oa, 0, 0, 0);
;   ob = __builtin_amdgcn_mfma_f32_32x32x16_bf16(pa3, PK(T.t[14], T.t[15]), ob, 0, 0, 0);
; __device__ __forceinline__ void attn_dv256_body(const bf16* __restrict__ Qb, const bf16* __restrict__ Kh, const bf16* __restrict__ Vh,
;                                                 float* __restrict__ Ob, int seq, float kmax, char* lds) {
;     ...
;     __syncthreads();
;     VWRITE(b ^ 1);
;     { const int kt = (j + 3 < NT) ? j + 3 : NT - 1, vt = (j + 2 < NT) ? j + 2 : NT - 1; KLOAD(kt * KVBLK); VLOAD(vt * KVBLK); }
;     q0 = own0; q1 = own1;
;     q2 = *(const bf16x8*)(XC0 + b * 16384 + (((wid ^ 4) * 2 + 0) * 64 + lane) * 16); q3 = *(const bf16x8*)(XC0 + b * 16384 + (((wid ^ 4) * 2 + 1) * 64 + lane) * 16);
;     pc = pn;
;   }
;   { PvT T; const int vl = vb0 + ((NT - 1) & 1) * 32768;
;     pv2_issue<2, 3>(T, vl); pv2_mma(o[2], o[3], T, q0, q1, q2, q3); pv2_issue<0, 1>(T, vl); pv2_mma(o[0], o[1], T, q0, q1, q2, q3); }
;   l_reg += __shfl_xor(l_reg, 32);
;   if (hi == 0) LI[kh * 128 + rg * 32 + r32] = l_reg;
	s_waitcnt vmcnt(0)
	ds_write_b128 v136, v[116:119]
	ds_write_b128 v137, v[112:115]
	v_add_u32_e32 v112, s1, v189
	v_add_u32_e32 v114, s1, v190
	v_add_u32_e32 v116, s13, v189
	ds_write_b128 v137, v[120:123] offset:16384
	ds_write_b128 v136, v[124:127] offset:16384
	v_add_u32_e32 v117, s13, v190
	v_mad_i64_i32 v[112:113], s[22:23], v112, s93, v[166:167]
	v_mad_i64_i32 v[114:115], s[22:23], v114, s93, v[166:167]
	v_mad_i64_i32 v[120:121], s[22:23], v116, s93, v[168:169]
	v_mad_i64_i32 v[124:125], s[22:23], v117, s93, v[168:169]
	global_load_dwordx4 v[136:139], v[112:113], off
	global_load_dwordx4 v[140:143], v[114:115], off
	s_nop 0
	global_load_dwordx4 v[112:115], v[124:125], off
	global_load_dwordx4 v[116:119], v[120:121], off
	s_nop 0
	global_load_dwordx4 v[120:123], v[120:121], off offset:256
	v_mfma_f32_32x32x16_bf16 v[0:15], v[144:147], v[210:213], v[0:15]
	global_load_dwordx4 v[124:127], v[124:125], off offset:256
	s_add_i32 s7, s7, 1
	s_cmp_eq_u32 s6, s7
	v_mfma_f32_32x32x16_bf16 v[16:31], v[144:147], v[226:229], v[16:31]
	v_mov_b32_e32 v144, v238
	v_mov_b32_e32 v145, v239
	v_mov_b32_e32 v146, v240
	v_mov_b32_e32 v147, v241
	v_mfma_f32_32x32x16_bf16 v[0:15], v[148:151], v[214:217], v[0:15]
	v_mfma_f32_32x32x16_bf16 v[16:31], v[148:151], v[230:233], v[16:31]
	v_mov_b32_e32 v149, v243
	v_mov_b32_e32 v150, v244
	v_mov_b32_e32 v151, v245
	v_mfma_f32_32x32x16_bf16 v[0:15], v[132:135], v[218:221], v[0:15]
	v_mfma_f32_32x32x16_bf16 v[16:31], v[132:135], v[234:237], v[16:31]
	v_bitop3_b32 v132, v209, s95, v205 bitop3:0x36
	v_add_u32_e32 v148, s35, v132
	v_mfma_f32_32x32x16_bf16 v[0:15], v[128:131], v[222:225], v[0:15]
	v_mfma_f32_32x32x16_bf16 v[16:31], v[128:131], v[160:163], v[16:31]
	ds_read_b128 v[132:135], v148
	ds_read_b128 v[128:131], v148 offset:1024
	v_mov_b32_e32 v148, v242
	s_cbranch_scc0 .LBB0_910
	v_mov_b32_e32 v152, v238
	v_mov_b32_e32 v153, v239
	v_mov_b32_e32 v154, v240
	v_mov_b32_e32 v155, v241
	v_mov_b32_e32 v156, v242
	v_mov_b32_e32 v157, v243
	v_mov_b32_e32 v158, v244
	v_mov_b32_e32 v159, v245
	v_add_u32_e32 v96, 0x8000, v207
	ds_read_b64_tr_b16 v[64:65], v96 offset:0x400
	ds_read_b64_tr_b16 v[66:67], v96 offset:0xc00
	ds_read_b64_tr_b16 v[68:69], v96 offset:0x1400
	ds_read_b64_tr_b16 v[70:71], v96 offset:0x1c00
	ds_read_b64_tr_b16 v[72:73], v96 offset:0x2400
	ds_read_b64_tr_b16 v[74:75], v96 offset:0x2c00
	ds_read_b64_tr_b16 v[76:77], v96 offset:0x3400
	ds_read_b64_tr_b16 v[78:79], v96 offset:0x3c00
	ds_read_b64_tr_b16 v[80:81], v96 offset:0x600
	ds_read_b64_tr_b16 v[82:83], v96 offset:0xe00
	ds_read_b64_tr_b16 v[84:85], v96 offset:0x1600
	ds_read_b64_tr_b16 v[86:87], v96 offset:0x1e00
	ds_read_b64_tr_b16 v[88:89], v96 offset:0x2600
	ds_read_b64_tr_b16 v[90:91], v96 offset:0x2e00
	ds_read_b64_tr_b16 v[92:93], v96 offset:0x3600
	ds_read_b64_tr_b16 v[94:95], v96 offset:0x3e00
	s_waitcnt lgkmcnt(0)
	s_nop 0
	v_mfma_f32_32x32x16_bf16 v[32:47], v[152:155], v[64:67], v[32:47]
	ds_read_b64_tr_b16 v[64:65], v96 offset:0
	ds_read_b64_tr_b16 v[66:67], v96 offset:0x800
	v_mfma_f32_32x32x16_bf16 v[48:63], v[152:155], v[80:83], v[48:63]
	v_mfma_f32_32x32x16_bf16 v[32:47], v[156:159], v[68:71], v[32:47]
	ds_read_b64_tr_b16 v[68:69], v96 offset:0x1000
	ds_read_b64_tr_b16 v[70:71], v96 offset:0x1800
	v_mfma_f32_32x32x16_bf16 v[48:63], v[156:159], v[84:87], v[48:63]
	s_waitcnt lgkmcnt(1)
	v_mfma_f32_32x32x16_bf16 v[32:47], v[132:135], v[72:75], v[32:47]
	ds_read_b64_tr_b16 v[72:73], v96 offset:0x2000
	ds_read_b64_tr_b16 v[74:75], v96 offset:0x2800
	v_mfma_f32_32x32x16_bf16 v[48:63], v[132:135], v[88:91], v[48:63]
	s_waitcnt lgkmcnt(0)
	v_mfma_f32_32x32x16_bf16 v[32:47], v[128:131], v[76:79], v[32:47]
	ds_read_b64_tr_b16 v[76:77], v96 offset:0x3000
	ds_read_b64_tr_b16 v[78:79], v96 offset:0x3800
	ds_read_b64_tr_b16 v[80:81], v96 offset:0x200
	ds_read_b64_tr_b16 v[82:83], v96 offset:0xa00
	ds_read_b64_tr_b16 v[84:85], v96 offset:0x1200
	ds_read_b64_tr_b16 v[86:87], v96 offset:0x1a00
	ds_read_b64_tr_b16 v[88:89], v96 offset:0x2200
	v_mfma_f32_32x32x16_bf16 v[48:63], v[128:131], v[92:95], v[48:63]
	ds_read_b64_tr_b16 v[90:91], v96 offset:0x2a00
	ds_read_b64_tr_b16 v[92:93], v96 offset:0x3200
	ds_read_b64_tr_b16 v[94:95], v96 offset:0x3a00
	s_waitcnt lgkmcnt(0)
	v_mfma_f32_32x32x16_bf16 v[0:15], v[152:155], v[64:67], v[0:15]
	ds_bpermute_b32 v66, v188, v192
	v_cmp_gt_u32_e32 vcc, 32, v191
	v_lshlrev_b32_e32 v65, 2, v185
	v_lshlrev_b32_e32 v64, 2, v186
	v_mfma_f32_32x32x16_bf16 v[16:31], v[152:155], v[80:83], v[16:31]
	v_mfma_f32_32x32x16_bf16 v[0:15], v[156:159], v[68:71], v[0:15]
	v_mfma_f32_32x32x16_bf16 v[16:31], v[156:159], v[84:87], v[16:31]
	v_mfma_f32_32x32x16_bf16 v[0:15], v[132:135], v[72:75], v[0:15]
	v_mfma_f32_32x32x16_bf16 v[16:31], v[132:135], v[88:91], v[16:31]
	v_mfma_f32_32x32x16_bf16 v[0:15], v[128:131], v[76:79], v[0:15]
	v_mfma_f32_32x32x16_bf16 v[16:31], v[128:131], v[92:95], v[16:31]
	s_and_saveexec_b64 s[0:1], vcc
	s_cbranch_execz .LBB0_913
	s_add_i32 s6, 0, 0x20000
	v_lshl_add_u32 v67, v187, 9, s6
	v_add3_u32 v67, v67, v65, v64
	s_waitcnt lgkmcnt(0)
	v_add_f32_e32 v66, v192, v66
	ds_write_b32 v67, v66
